# v44 with one (not two) early decode pull on group 0 of the non-preparing workgroups
# speedup vs baseline: 1.0273x; 1.0188x over previous
; #define LAS __attribute__((address_space(3)))
; __device__ __forceinline__ void sb_decode_wave_loop(const Params& P, float* lds) {
;     unsigned* qd = (unsigned*)(P.ws + WS_BAR) + QW_DEC;
;     const int lane = threadIdx.x & 63;
;     volatile LAS unsigned* scw = (volatile LAS unsigned*)((LAS unsigned char*)lds + SC_CTL_OFF_FWD);
;     unsigned nxt = 0u;
;     if (lane == 0) nxt = atomicAdd(qd, 2u);
; __device__ __forceinline__ void p3_scan_and_sb(const Params& P, float* lds) {
;     ...
;     } else {
;         const int grp = wave >> 2, gw = wave & 3;
;         volatile LAS unsigned* gctl = (volatile LAS unsigned*)((LAS unsigned char*)lds + LDS_CTL + 32);
;         if (tid < 8) gctl[tid] = 0u;
;         __syncthreads();
;         sba::Grp4 G; G.ctr = gctl + grp; G.gen = 0u;
;         if (grp == 1) sb_decode_wave_loop(P, lds);
.LBB0_939:
	s_cmp_lt_i32 s60, 4
	s_cselect_b64 s[0:1], -1, 0
	s_cmp_gt_i32 s61, 3
	s_cselect_b64 s[2:3], -1, 0
	s_and_b64 s[34:35], s[0:1], s[2:3]
	s_andn2_b64 vcc, exec, s[34:35]
	s_cbranch_vccnz .LBB0_1576
	v_writelane_b32 v252, s34, 54
	s_cmpk_lt_u32 s56, 0x60
	v_and_b32_e32 v1, 63, v0
	v_writelane_b32 v252, s35, 55
	v_writelane_b32 v252, s80, 56
	s_cselect_b64 s[52:53], -1, 0
	s_cmpk_gt_u32 s56, 0x5f
	v_writelane_b32 v252, s81, 57
	v_writelane_b32 v252, s56, 53
	v_writelane_b32 v252, s60, 51
	s_mov_b64 s[0:1], -1
	s_waitcnt vmcnt(0)
	v_writelane_b32 v252, s61, 52
	s_barrier
	v_writelane_b32 v252, s57, 50
	s_cbranch_scc0 .LBB0_1203
	v_writelane_b32 v252, s52, 58
	v_cmp_gt_u32_e32 vcc, 8, v0
	s_nop 0
	v_writelane_b32 v252, s53, 59
	s_and_saveexec_b64 s[0:1], vcc
	v_lshl_add_u32 v2, v0, 2, 0
	v_add_u32_e32 v2, 0x26020, v2
	v_mov_b32_e32 v3, 0
	ds_write_b32 v2, v3
	s_or_b64 exec, exec, s[0:1]
	v_lshrrev_b32_e32 v94, 8, v0
	s_waitcnt lgkmcnt(0)
	s_barrier
	v_cmp_eq_u32_e32 vcc, 1, v94
	s_mov_b64 s[0:1], exec
	v_writelane_b32 v252, s0, 60
	s_nop 1
	v_writelane_b32 v252, s1, 61
	s_cmpk_gt_u32 s56, 0xaa
	s_cselect_b64 s[2:3], exec, 0
	s_or_b64 vcc, vcc, s[2:3]
	s_and_b64 s[0:1], s[0:1], vcc
	s_mov_b64 exec, s[0:1]
	s_cbranch_execz .LBB0_1092
	v_readfirstlane_b32 s2, v94
	s_cmp_eq_u32 s2, 0
	s_cselect_b32 s100, 0, 0x7fffffff
	s_add_u32 s0, s78, 0x3900
	s_addc_u32 s1, s79, 0
	v_writelane_b32 v252, s0, 62
	v_mov_b32_e32 v95, 0
	v_cmp_eq_u32_e64 s[4:5], 0, v1
	v_writelane_b32 v252, s1, 63
	s_and_saveexec_b64 s[0:1], s[4:5]
	v_readlane_b32 s22, v252, 48
	v_readlane_b32 s23, v252, 49
	s_cbranch_execz .LBB0_948
	s_mov_b64 s[6:7], exec
	v_mbcnt_lo_u32_b32 v2, s6, 0
	v_mbcnt_hi_u32_b32 v2, s7, v2
	v_cmp_eq_u32_e32 vcc, 0, v2
	s_and_saveexec_b64 s[2:3], vcc
	s_cbranch_execz .LBB0_947
	s_bcnt1_i32_b64 s6, s[6:7]
	s_lshl_b32 s6, s6, 1
	v_mov_b32_e32 v4, s6
	v_readlane_b32 s6, v252, 62
	v_mov_b32_e32 v3, 0
	v_readlane_b32 s7, v252, 63
	s_nop 4
	global_atomic_add v3, v3, v4, s[6:7] sc0
